# kv_tile GEMMs: next tile's global loads issued right after the LDS stores (same as q_tile), one more iteration of latency cover
# speedup vs baseline: 1.0012x; 1.0012x over previous
; #define MFMA(a, b, c) __builtin_amdgcn_mfma_f32_32x32x16_bf16((a), (b), (c), 0, 0, 0)
; template <int BM, int BN, int BK, int WAVES_M, int WAVES_N, int UNSWAP_FROM>
; DI void gemm_mainloop(const int tid, const bf16_t* __restrict__ A, int lda, const bf16_t* __restrict__ Bt, int ldb, int K, unsigned char* smem,
;                       f32x16 (&acc)[BM / WAVES_M / 32][BN / WAVES_N / 32]) {
;     ...
;     for (int kt = 0; kt < nk; ++kt) {
;         const int buf = kt & 1;
;         if (kt + 1 < nk) G_LOAD(kt + 1);
;         const unsigned char* sa_ = smem + buf * STAGE; const unsigned char* sb_ = sa_ + A_ST;
; #pragma unroll
;         for (int ks = 0; ks < BK / 16; ++ks) {
;             bf16x8 af[WM], bfr[WN];
; #pragma unroll
;             for (int i = 0; i < WM; ++i) af[i] = *(const bf16x8*)(sa_ + (((wm * WM + i) * 32 + r) * LS + ks * 16 + h * 8) * 2);
; #pragma unroll
;             for (int j = 0; j < WN; ++j) bfr[j] = *(const bf16x8*)(sb_ + (((wn * WN + j) * 32 + r) * LS + ks * 16 + h * 8) * 2);
; #pragma unroll
;             for (int i = 0; i < WM; ++i)
; #pragma unroll
;                 for (int j = 0; j < WN; ++j) {
;                     if (j < UNSWAP_FROM) acc[i][j] = MFMA(bfr[j], af[i], acc[i][j]);
;                     else acc[i][j] = MFMA(af[i], bfr[j], acc[i][j]);
;                 }
;         }
;         if (kt + 1 < nk) G_STORE(buf ^ 1);
;         __syncthreads();
.Lkv_stg_beg0:
	global_load_dwordx4 v[80:83], v[66:67], off offset:1088
	global_load_dwordx4 v[84:87], v[68:69], off offset:1088
	v_lshl_add_u64 v[0:1], v[0:1], 0, v[72:73]
	global_load_dwordx4 v[88:91], v[0:1], off
	v_lshl_add_u64 v[0:1], s[4:5], 0, v[74:75]
	v_lshl_add_u64 v[0:1], v[0:1], 0, v[70:71]
	global_load_dwordx4 v[98:101], v[0:1], off
	v_mul_u32_u24_e32 v4, 0x50, v92
	s_add_u32 s4, s74, 0x10080
	v_add3_u32 v95, v2, v4, s10
	s_addc_u32 s5, s75, 0
	v_add3_u32 v96, v3, v2, s10
	ds_read_b128 v[0:3], v95 offset:12800
	ds_read_b128 v[4:7], v95 offset:15360
	ds_read_b128 v[8:11], v95 offset:17920
	ds_read_b128 v[12:15], v96
	ds_read_b128 v[102:105], v96 offset:32
	ds_read_b128 v[16:19], v95 offset:10240
	ds_read_b128 v[106:109], v95 offset:10272
	ds_read_b128 v[110:113], v95 offset:12832
	ds_read_b128 v[120:123], v95 offset:15392
	ds_read_b128 v[124:127], v95 offset:17952
	s_waitcnt lgkmcnt(4)
	v_mfma_f32_32x32x16_bf16 v[48:63], v[12:15], v[16:19], 0
	s_barrier
	s_waitcnt vmcnt(3)
	ds_write_b128 v93, v[80:83] offset:20480
	s_waitcnt vmcnt(2)
	ds_write_b128 v94, v[84:87] offset:20480
	s_waitcnt vmcnt(1)
	ds_write_b128 v93, v[88:91] offset:30720
	s_waitcnt vmcnt(0)
	ds_write_b128 v94, v[98:101] offset:30720
	global_load_dwordx4 v[80:83], v[66:67], off offset:1152
	global_load_dwordx4 v[84:87], v[68:69], off offset:1152
	v_lshl_add_u64 v[88:89], s[4:5], 0, v[76:77]
	v_lshl_add_u64 v[88:89], v[88:89], 0, v[72:73]
	v_lshl_add_u64 v[98:99], s[4:5], 0, v[74:75]
	global_load_dwordx4 v[88:91], v[88:89], off
	v_lshl_add_u64 v[98:99], v[98:99], 0, v[70:71]
	global_load_dwordx4 v[98:101], v[98:99], off
	s_waitcnt lgkmcnt(0)
	s_barrier
	v_mfma_f32_32x32x16_bf16 v[32:47], v[12:15], v[0:3], 0
	s_add_u32 s4, s74, 0x100c0
	s_addc_u32 s5, s75, 0
	v_mfma_f32_32x32x16_bf16 v[16:31], v[12:15], v[4:7], 0
	v_mfma_f32_32x32x16_bf16 v[0:15], v[12:15], v[8:11], 0
	v_mfma_f32_32x32x16_bf16 v[32:47], v[102:105], v[110:113], v[32:47]
	v_mfma_f32_32x32x16_bf16 v[16:31], v[102:105], v[120:123], v[16:31]
	v_mfma_f32_32x32x16_bf16 v[0:15], v[102:105], v[124:127], v[0:15]
	v_mfma_f32_32x32x16_bf16 v[48:63], v[102:105], v[106:109], v[48:63]
	ds_read_b128 v[102:105], v95 offset:33280
	ds_read_b128 v[106:109], v95 offset:35840
	ds_read_b128 v[110:113], v95 offset:38400
	ds_read_b128 v[120:123], v96 offset:20480
	ds_read_b128 v[124:127], v96 offset:20512
	ds_read_b128 v[128:131], v95 offset:30720
	ds_read_b128 v[132:135], v95 offset:30752
	s_waitcnt lgkmcnt(3)
	v_mfma_f32_32x32x16_bf16 v[32:47], v[120:123], v[102:105], v[32:47]
	v_mfma_f32_32x32x16_bf16 v[16:31], v[120:123], v[106:109], v[16:31]
	v_mfma_f32_32x32x16_bf16 v[0:15], v[120:123], v[110:113], v[0:15]
	ds_read_b128 v[102:105], v95 offset:33312
	ds_read_b128 v[106:109], v95 offset:35872
	ds_read_b128 v[110:113], v95 offset:38432
	s_barrier
	s_waitcnt vmcnt(3)
	ds_write_b128 v93, v[80:83]
	s_waitcnt vmcnt(2)
	ds_write_b128 v94, v[84:87]
	s_waitcnt vmcnt(1)
	ds_write_b128 v93, v[88:91] offset:10240
	s_waitcnt vmcnt(0)
	ds_write_b128 v94, v[98:101] offset:10240
	global_load_dwordx4 v[80:83], v[66:67], off offset:1216
	global_load_dwordx4 v[84:87], v[68:69], off offset:1216
	v_lshl_add_u64 v[88:89], s[4:5], 0, v[76:77]
	v_lshl_add_u64 v[88:89], v[88:89], 0, v[72:73]
	v_lshl_add_u64 v[98:99], s[4:5], 0, v[74:75]
	global_load_dwordx4 v[88:91], v[88:89], off
	v_lshl_add_u64 v[98:99], v[98:99], 0, v[70:71]
	global_load_dwordx4 v[98:101], v[98:99], off
	s_waitcnt lgkmcnt(0)
	s_barrier
	v_mfma_f32_32x32x16_bf16 v[48:63], v[120:123], v[128:131], v[48:63]
	s_add_u32 s4, s74, 0x10100
	s_addc_u32 s5, s75, 0
	v_mfma_f32_32x32x16_bf16 v[32:47], v[124:127], v[102:105], v[32:47]
	v_mfma_f32_32x32x16_bf16 v[16:31], v[124:127], v[106:109], v[16:31]
	v_mfma_f32_32x32x16_bf16 v[0:15], v[124:127], v[110:113], v[0:15]
	v_mfma_f32_32x32x16_bf16 v[48:63], v[124:127], v[132:135], v[48:63]
	ds_read_b128 v[102:105], v95 offset:12800
	ds_read_b128 v[106:109], v95 offset:15360
	ds_read_b128 v[110:113], v95 offset:17920
	ds_read_b128 v[120:123], v96
	ds_read_b128 v[124:127], v96 offset:32
	ds_read_b128 v[128:131], v95 offset:10240
	ds_read_b128 v[132:135], v95 offset:10272
	s_waitcnt lgkmcnt(3)
	v_mfma_f32_32x32x16_bf16 v[32:47], v[120:123], v[102:105], v[32:47]
	v_mfma_f32_32x32x16_bf16 v[16:31], v[120:123], v[106:109], v[16:31]
	v_mfma_f32_32x32x16_bf16 v[0:15], v[120:123], v[110:113], v[0:15]
	ds_read_b128 v[102:105], v95 offset:12832
	ds_read_b128 v[106:109], v95 offset:15392
	ds_read_b128 v[110:113], v95 offset:17952
	s_barrier
	s_waitcnt vmcnt(3)
	ds_write_b128 v93, v[80:83] offset:20480
	s_waitcnt vmcnt(2)
	ds_write_b128 v94, v[84:87] offset:20480
	s_waitcnt vmcnt(1)
	ds_write_b128 v93, v[88:91] offset:30720
	s_waitcnt vmcnt(0)
	ds_write_b128 v94, v[98:101] offset:30720
	global_load_dwordx4 v[80:83], v[66:67], off offset:1280
	global_load_dwordx4 v[84:87], v[68:69], off offset:1280
	v_lshl_add_u64 v[88:89], s[4:5], 0, v[76:77]
	v_lshl_add_u64 v[88:89], v[88:89], 0, v[72:73]
	v_lshl_add_u64 v[98:99], s[4:5], 0, v[74:75]
	global_load_dwordx4 v[88:91], v[88:89], off
	v_lshl_add_u64 v[98:99], v[98:99], 0, v[70:71]
	global_load_dwordx4 v[98:101], v[98:99], off
	s_waitcnt lgkmcnt(0)
	s_barrier
; #define MFMA(a, b, c) __builtin_amdgcn_mfma_f32_32x32x16_bf16((a), (b), (c), 0, 0, 0)
; template <int BM, int BN, int BK, int WAVES_M, int WAVES_N, int UNSWAP_FROM>
; DI void gemm_mainloop(const int tid, const bf16_t* __restrict__ A, int lda, const bf16_t* __restrict__ Bt, int ldb, int K, unsigned char* smem,
;                       f32x16 (&acc)[BM / WAVES_M / 32][BN / WAVES_N / 32]) {
;     ...
;     G_LOAD(0); G_STORE(0); __syncthreads();
;     for (int kt = 0; kt < nk; ++kt) {
;         const int buf = kt & 1;
;         if (kt + 1 < nk) G_LOAD(kt + 1);
;         const unsigned char* sa_ = smem + buf * STAGE; const unsigned char* sb_ = sa_ + A_ST;
; #pragma unroll
;         for (int ks = 0; ks < BK / 16; ++ks) {
;             bf16x8 af[WM], bfr[WN];
; #pragma unroll
;             for (int i = 0; i < WM; ++i) af[i] = *(const bf16x8*)(sa_ + (((wm * WM + i) * 32 + r) * LS + ks * 16 + h * 8) * 2);
; #pragma unroll
;             for (int j = 0; j < WN; ++j) bfr[j] = *(const bf16x8*)(sb_ + (((wn * WN + j) * 32 + r) * LS + ks * 16 + h * 8) * 2);
; #pragma unroll
;             for (int i = 0; i < WM; ++i)
; #pragma unroll
;                 for (int j = 0; j < WN; ++j) {
;                     if (j < UNSWAP_FROM) acc[i][j] = MFMA(bfr[j], af[i], acc[i][j]);
;                     else acc[i][j] = MFMA(af[i], bfr[j], acc[i][j]);
;                 }
;         }
;         if (kt + 1 < nk) G_STORE(buf ^ 1);
;         __syncthreads();
;     }
	v_mfma_f32_32x32x16_bf16 v[48:63], v[120:123], v[128:131], v[48:63]
	s_add_u32 s4, s74, 0x10140
	s_addc_u32 s5, s75, 0
	v_mfma_f32_32x32x16_bf16 v[32:47], v[124:127], v[102:105], v[32:47]
	v_mfma_f32_32x32x16_bf16 v[16:31], v[124:127], v[106:109], v[16:31]
	v_mfma_f32_32x32x16_bf16 v[0:15], v[124:127], v[110:113], v[0:15]
	v_mfma_f32_32x32x16_bf16 v[48:63], v[124:127], v[132:135], v[48:63]
	ds_read_b128 v[102:105], v95 offset:33280
	ds_read_b128 v[106:109], v95 offset:35840
	ds_read_b128 v[110:113], v95 offset:38400
	ds_read_b128 v[120:123], v96 offset:20480
	ds_read_b128 v[124:127], v96 offset:20512
	ds_read_b128 v[128:131], v95 offset:30720
	ds_read_b128 v[132:135], v95 offset:30752
	s_waitcnt lgkmcnt(3)
	v_mfma_f32_32x32x16_bf16 v[32:47], v[120:123], v[102:105], v[32:47]
	v_mfma_f32_32x32x16_bf16 v[16:31], v[120:123], v[106:109], v[16:31]
	v_mfma_f32_32x32x16_bf16 v[0:15], v[120:123], v[110:113], v[0:15]
	ds_read_b128 v[102:105], v95 offset:33312
	ds_read_b128 v[106:109], v95 offset:35872
	ds_read_b128 v[110:113], v95 offset:38432
	s_barrier
	s_waitcnt vmcnt(3)
	ds_write_b128 v93, v[80:83]
	s_waitcnt vmcnt(2)
	ds_write_b128 v94, v[84:87]
	s_waitcnt vmcnt(1)
	ds_write_b128 v93, v[88:91] offset:10240
	s_waitcnt vmcnt(0)
	ds_write_b128 v94, v[98:101] offset:10240
	global_load_dwordx4 v[80:83], v[66:67], off offset:1344
	global_load_dwordx4 v[84:87], v[68:69], off offset:1344
	v_lshl_add_u64 v[88:89], s[4:5], 0, v[76:77]
	v_lshl_add_u64 v[88:89], v[88:89], 0, v[72:73]
	v_lshl_add_u64 v[98:99], s[4:5], 0, v[74:75]
	global_load_dwordx4 v[88:91], v[88:89], off
	v_lshl_add_u64 v[98:99], v[98:99], 0, v[70:71]
	global_load_dwordx4 v[98:101], v[98:99], off
	s_waitcnt lgkmcnt(0)
	s_barrier
	v_mfma_f32_32x32x16_bf16 v[48:63], v[120:123], v[128:131], v[48:63]
	s_add_u32 s4, s74, 0x10180
	s_addc_u32 s5, s75, 0
	v_mfma_f32_32x32x16_bf16 v[32:47], v[124:127], v[102:105], v[32:47]
	v_mfma_f32_32x32x16_bf16 v[16:31], v[124:127], v[106:109], v[16:31]
	v_mfma_f32_32x32x16_bf16 v[0:15], v[124:127], v[110:113], v[0:15]
	v_mfma_f32_32x32x16_bf16 v[48:63], v[124:127], v[132:135], v[48:63]
	ds_read_b128 v[102:105], v95 offset:12800
	ds_read_b128 v[106:109], v95 offset:15360
	ds_read_b128 v[110:113], v95 offset:17920
	ds_read_b128 v[120:123], v96
	ds_read_b128 v[124:127], v96 offset:32
	ds_read_b128 v[128:131], v95 offset:10240
	ds_read_b128 v[132:135], v95 offset:10272
	s_waitcnt lgkmcnt(3)
	v_mfma_f32_32x32x16_bf16 v[32:47], v[120:123], v[102:105], v[32:47]
	v_mfma_f32_32x32x16_bf16 v[16:31], v[120:123], v[106:109], v[16:31]
	v_mfma_f32_32x32x16_bf16 v[0:15], v[120:123], v[110:113], v[0:15]
	ds_read_b128 v[102:105], v95 offset:12832
	ds_read_b128 v[106:109], v95 offset:15392
	ds_read_b128 v[110:113], v95 offset:17952
	s_barrier
	s_waitcnt vmcnt(3)
	ds_write_b128 v93, v[80:83] offset:20480
	s_waitcnt vmcnt(2)
	ds_write_b128 v94, v[84:87] offset:20480
	s_waitcnt vmcnt(1)
	ds_write_b128 v93, v[88:91] offset:30720
	s_waitcnt vmcnt(0)
	ds_write_b128 v94, v[98:101] offset:30720
	global_load_dwordx4 v[80:83], v[66:67], off offset:1408
	global_load_dwordx4 v[84:87], v[68:69], off offset:1408
	v_lshl_add_u64 v[88:89], s[4:5], 0, v[76:77]
	v_lshl_add_u64 v[88:89], v[88:89], 0, v[72:73]
	v_lshl_add_u64 v[98:99], s[4:5], 0, v[74:75]
	global_load_dwordx4 v[88:91], v[88:89], off
	v_lshl_add_u64 v[98:99], v[98:99], 0, v[70:71]
	global_load_dwordx4 v[98:101], v[98:99], off
	s_waitcnt lgkmcnt(0)
	s_barrier
; #define MFMA(a, b, c) __builtin_amdgcn_mfma_f32_32x32x16_bf16((a), (b), (c), 0, 0, 0)
; template <int BM, int BN, int BK, int WAVES_M, int WAVES_N, int UNSWAP_FROM>
; DI void gemm_mainloop(const int tid, const bf16_t* __restrict__ A, int lda, const bf16_t* __restrict__ Bt, int ldb, int K, unsigned char* smem,
;                       f32x16 (&acc)[BM / WAVES_M / 32][BN / WAVES_N / 32]) {
;     ...
;     for (int kt = 0; kt < nk; ++kt) {
;         const int buf = kt & 1;
;         if (kt + 1 < nk) G_LOAD(kt + 1);
;         const unsigned char* sa_ = smem + buf * STAGE; const unsigned char* sb_ = sa_ + A_ST;
; #pragma unroll
;         for (int ks = 0; ks < BK / 16; ++ks) {
;             bf16x8 af[WM], bfr[WN];
; #pragma unroll
;             for (int i = 0; i < WM; ++i) af[i] = *(const bf16x8*)(sa_ + (((wm * WM + i) * 32 + r) * LS + ks * 16 + h * 8) * 2);
; #pragma unroll
;             for (int j = 0; j < WN; ++j) bfr[j] = *(const bf16x8*)(sb_ + (((wn * WN + j) * 32 + r) * LS + ks * 16 + h * 8) * 2);
; #pragma unroll
;             for (int i = 0; i < WM; ++i)
; #pragma unroll
;                 for (int j = 0; j < WN; ++j) {
;                     if (j < UNSWAP_FROM) acc[i][j] = MFMA(bfr[j], af[i], acc[i][j]);
;                     else acc[i][j] = MFMA(af[i], bfr[j], acc[i][j]);
;                 }
;         }
;         if (kt + 1 < nk) G_STORE(buf ^ 1);
;         __syncthreads();
;     }
	v_mfma_f32_32x32x16_bf16 v[48:63], v[120:123], v[128:131], v[48:63]
	s_add_u32 s4, s74, 0x101c0
	s_addc_u32 s5, s75, 0
	v_mfma_f32_32x32x16_bf16 v[32:47], v[124:127], v[102:105], v[32:47]
	v_mfma_f32_32x32x16_bf16 v[16:31], v[124:127], v[106:109], v[16:31]
	v_mfma_f32_32x32x16_bf16 v[0:15], v[124:127], v[110:113], v[0:15]
	v_mfma_f32_32x32x16_bf16 v[48:63], v[124:127], v[132:135], v[48:63]
	ds_read_b128 v[102:105], v95 offset:33280
	ds_read_b128 v[106:109], v95 offset:35840
	ds_read_b128 v[110:113], v95 offset:38400
	ds_read_b128 v[120:123], v96 offset:20480
	ds_read_b128 v[124:127], v96 offset:20512
	ds_read_b128 v[128:131], v95 offset:30720
	ds_read_b128 v[132:135], v95 offset:30752
	s_waitcnt lgkmcnt(3)
	v_mfma_f32_32x32x16_bf16 v[32:47], v[120:123], v[102:105], v[32:47]
	v_mfma_f32_32x32x16_bf16 v[16:31], v[120:123], v[106:109], v[16:31]
	v_mfma_f32_32x32x16_bf16 v[0:15], v[120:123], v[110:113], v[0:15]
	ds_read_b128 v[102:105], v95 offset:33312
	ds_read_b128 v[106:109], v95 offset:35872
	ds_read_b128 v[110:113], v95 offset:38432
	s_barrier
	s_waitcnt vmcnt(3)
	ds_write_b128 v93, v[80:83]
	s_waitcnt vmcnt(2)
	ds_write_b128 v94, v[84:87]
	s_waitcnt vmcnt(1)
	ds_write_b128 v93, v[88:91] offset:10240
	s_waitcnt vmcnt(0)
	ds_write_b128 v94, v[98:101] offset:10240
	global_load_dwordx4 v[80:83], v[66:67], off offset:1472
	global_load_dwordx4 v[84:87], v[68:69], off offset:1472
	v_lshl_add_u64 v[88:89], s[4:5], 0, v[76:77]
	v_lshl_add_u64 v[88:89], v[88:89], 0, v[72:73]
	v_lshl_add_u64 v[98:99], s[4:5], 0, v[74:75]
	global_load_dwordx4 v[88:91], v[88:89], off
	v_lshl_add_u64 v[98:99], v[98:99], 0, v[70:71]
	global_load_dwordx4 v[98:101], v[98:99], off
	s_waitcnt lgkmcnt(0)
	s_barrier
	v_mfma_f32_32x32x16_bf16 v[48:63], v[120:123], v[128:131], v[48:63]
	v_readlane_b32 s4, v244, 29
	v_readlane_b32 s5, v244, 30
	v_mfma_f32_32x32x16_bf16 v[32:47], v[124:127], v[102:105], v[32:47]
	v_mfma_f32_32x32x16_bf16 v[0:15], v[124:127], v[110:113], v[0:15]
	v_mfma_f32_32x32x16_bf16 v[16:31], v[124:127], v[106:109], v[16:31]
	v_mfma_f32_32x32x16_bf16 v[48:63], v[124:127], v[132:135], v[48:63]
	ds_read_b128 v[102:105], v95 offset:12800
	ds_read_b128 v[106:109], v95 offset:15360
	ds_read_b128 v[110:113], v95 offset:17920
	ds_read_b128 v[120:123], v96
	ds_read_b128 v[124:127], v96 offset:32
	ds_read_b128 v[128:131], v95 offset:10240
	ds_read_b128 v[132:135], v95 offset:10272
	s_waitcnt lgkmcnt(3)
	v_mfma_f32_32x32x16_bf16 v[32:47], v[120:123], v[102:105], v[32:47]
	v_mfma_f32_32x32x16_bf16 v[0:15], v[120:123], v[110:113], v[0:15]
	v_mfma_f32_32x32x16_bf16 v[16:31], v[120:123], v[106:109], v[16:31]
	ds_read_b128 v[102:105], v95 offset:12832
	ds_read_b128 v[106:109], v95 offset:15392
	ds_read_b128 v[110:113], v95 offset:17952
	s_barrier
	s_waitcnt vmcnt(3)
	ds_write_b128 v93, v[80:83] offset:20480
	s_waitcnt vmcnt(2)
	ds_write_b128 v94, v[84:87] offset:20480
	s_waitcnt vmcnt(1)
	ds_write_b128 v93, v[88:91] offset:30720
	s_waitcnt vmcnt(0)
	ds_write_b128 v94, v[98:101] offset:30720
	s_waitcnt lgkmcnt(6)
	v_mfma_f32_32x32x16_bf16 v[32:47], v[124:127], v[102:105], v[32:47]
	s_waitcnt lgkmcnt(0)
	s_barrier
	v_mfma_f32_32x32x16_bf16 v[0:15], v[124:127], v[110:113], v[0:15]
	v_mfma_f32_32x32x16_bf16 v[16:31], v[124:127], v[106:109], v[16:31]
	ds_read_b128 v[80:83], v95 offset:33280
	ds_read_b128 v[84:87], v95 offset:35840
	ds_read_b128 v[88:91], v95 offset:38400
	ds_read_b128 v[98:101], v96 offset:20480
	ds_read_b128 v[102:105], v96 offset:20512
	ds_read_b128 v[106:109], v95 offset:30720
	ds_read_b128 v[110:113], v95 offset:30752
	s_waitcnt lgkmcnt(3)
	v_mfma_f32_32x32x16_bf16 v[32:47], v[98:101], v[80:83], v[32:47]
	v_mfma_f32_32x32x16_bf16 v[0:15], v[98:101], v[88:91], v[0:15]
	v_mfma_f32_32x32x16_bf16 v[16:31], v[98:101], v[84:87], v[16:31]
	ds_read_b128 v[80:83], v95 offset:33312
	ds_read_b128 v[84:87], v95 offset:35872
	ds_read_b128 v[88:91], v95 offset:38432
	s_waitcnt lgkmcnt(0)
	s_barrier
	s_cmp_lg_u32 s10, 0
	s_cbranch_scc1 .Lkv_stg_end0
	s_barrier

; #define MFMA(a, b, c) __builtin_amdgcn_mfma_f32_32x32x16_bf16((a), (b), (c), 0, 0, 0)
; template <int BM, int BN, int BK, int WAVES_M, int WAVES_N, int UNSWAP_FROM>
; DI void gemm_mainloop(const int tid, const bf16_t* __restrict__ A, int lda, const bf16_t* __restrict__ Bt, int ldb, int K, unsigned char* smem,
;                       f32x16 (&acc)[BM / WAVES_M / 32][BN / WAVES_N / 32]) {
;     ...
;     G_LOAD(0); G_STORE(0); __syncthreads();
;     for (int kt = 0; kt < nk; ++kt) {
;         const int buf = kt & 1;
;         if (kt + 1 < nk) G_LOAD(kt + 1);
;         const unsigned char* sa_ = smem + buf * STAGE; const unsigned char* sb_ = sa_ + A_ST;
; #pragma unroll
;         for (int ks = 0; ks < BK / 16; ++ks) {
;             bf16x8 af[WM], bfr[WN];
; #pragma unroll
;             for (int i = 0; i < WM; ++i) af[i] = *(const bf16x8*)(sa_ + (((wm * WM + i) * 32 + r) * LS + ks * 16 + h * 8) * 2);
; #pragma unroll
;             for (int j = 0; j < WN; ++j) bfr[j] = *(const bf16x8*)(sb_ + (((wn * WN + j) * 32 + r) * LS + ks * 16 + h * 8) * 2);
; #pragma unroll
;             for (int i = 0; i < WM; ++i)
; #pragma unroll
;                 for (int j = 0; j < WN; ++j) {
;                     if (j < UNSWAP_FROM) acc[i][j] = MFMA(bfr[j], af[i], acc[i][j]);
;                     else acc[i][j] = MFMA(af[i], bfr[j], acc[i][j]);
;                 }
;         }
;         if (kt + 1 < nk) G_STORE(buf ^ 1);
;         __syncthreads();
;     }
.Lkv_stg_beg1:
	global_load_dwordx4 v[74:77], v[66:67], off offset:1088
	global_load_dwordx4 v[82:85], v[68:69], off offset:1088
	global_load_dwordx4 v[86:89], v[72:73], off offset:64
	global_load_dwordx4 v[98:101], v[70:71], off offset:64
	ds_read_b128 v[0:3], v95 offset:12800
	ds_read_b128 v[4:7], v95 offset:15360
	ds_read_b128 v[8:11], v95 offset:17920
	ds_read_b128 v[12:15], v96
	ds_read_b128 v[102:105], v96 offset:32
	ds_read_b128 v[16:19], v95 offset:10240
	ds_read_b128 v[106:109], v95 offset:10272
	ds_read_b128 v[110:113], v95 offset:12832
	ds_read_b128 v[120:123], v95 offset:15392
	ds_read_b128 v[124:127], v95 offset:17952
	s_barrier
	s_waitcnt vmcnt(3)
	ds_write_b128 v93, v[74:77] offset:20480
	s_waitcnt vmcnt(2)
	ds_write_b128 v94, v[82:85] offset:20480
	s_waitcnt vmcnt(1)
	ds_write_b128 v93, v[86:89] offset:30720
	s_waitcnt vmcnt(0)
	ds_write_b128 v94, v[98:101] offset:30720
	global_load_dwordx4 v[74:77], v[66:67], off offset:1152
	global_load_dwordx4 v[82:85], v[68:69], off offset:1152
	global_load_dwordx4 v[86:89], v[72:73], off offset:128
	global_load_dwordx4 v[98:101], v[70:71], off offset:128
	s_waitcnt lgkmcnt(0)
	s_barrier
	v_mfma_f32_32x32x16_bf16 v[48:63], v[16:19], v[12:15], 0
	v_mfma_f32_32x32x16_bf16 v[32:47], v[0:3], v[12:15], 0
	v_mfma_f32_32x32x16_bf16 v[16:31], v[4:7], v[12:15], 0
	v_mfma_f32_32x32x16_bf16 v[0:15], v[8:11], v[12:15], 0
	v_mfma_f32_32x32x16_bf16 v[32:47], v[110:113], v[102:105], v[32:47]
	v_mfma_f32_32x32x16_bf16 v[16:31], v[120:123], v[102:105], v[16:31]
	v_mfma_f32_32x32x16_bf16 v[0:15], v[124:127], v[102:105], v[0:15]
	v_mfma_f32_32x32x16_bf16 v[48:63], v[106:109], v[102:105], v[48:63]
	ds_read_b128 v[102:105], v95 offset:33280
	ds_read_b128 v[106:109], v95 offset:35840
	ds_read_b128 v[110:113], v95 offset:38400
	ds_read_b128 v[120:123], v96 offset:20480
	ds_read_b128 v[124:127], v96 offset:20512
	ds_read_b128 v[128:131], v95 offset:30720
	ds_read_b128 v[132:135], v95 offset:30752
	s_waitcnt lgkmcnt(3)
	v_mfma_f32_32x32x16_bf16 v[32:47], v[102:105], v[120:123], v[32:47]
	v_mfma_f32_32x32x16_bf16 v[16:31], v[106:109], v[120:123], v[16:31]
	v_mfma_f32_32x32x16_bf16 v[0:15], v[110:113], v[120:123], v[0:15]
	ds_read_b128 v[102:105], v95 offset:33312
	ds_read_b128 v[106:109], v95 offset:35872
	ds_read_b128 v[110:113], v95 offset:38432
	s_barrier
	s_waitcnt vmcnt(3)
	ds_write_b128 v93, v[74:77]
	s_waitcnt vmcnt(2)
	ds_write_b128 v94, v[82:85]
	s_waitcnt vmcnt(1)
	ds_write_b128 v93, v[86:89] offset:10240
	s_waitcnt vmcnt(0)
	ds_write_b128 v94, v[98:101] offset:10240
	global_load_dwordx4 v[74:77], v[66:67], off offset:1216
	global_load_dwordx4 v[82:85], v[68:69], off offset:1216
	global_load_dwordx4 v[86:89], v[72:73], off offset:192
	global_load_dwordx4 v[98:101], v[70:71], off offset:192
	s_waitcnt lgkmcnt(0)
	s_barrier
	v_mfma_f32_32x32x16_bf16 v[48:63], v[128:131], v[120:123], v[48:63]
	v_mfma_f32_32x32x16_bf16 v[32:47], v[102:105], v[124:127], v[32:47]
	v_mfma_f32_32x32x16_bf16 v[16:31], v[106:109], v[124:127], v[16:31]
	v_mfma_f32_32x32x16_bf16 v[0:15], v[110:113], v[124:127], v[0:15]
	v_mfma_f32_32x32x16_bf16 v[48:63], v[132:135], v[124:127], v[48:63]
	ds_read_b128 v[102:105], v95 offset:12800
	ds_read_b128 v[106:109], v95 offset:15360
	ds_read_b128 v[110:113], v95 offset:17920
	ds_read_b128 v[120:123], v96
	ds_read_b128 v[124:127], v96 offset:32
	ds_read_b128 v[128:131], v95 offset:10240
	ds_read_b128 v[132:135], v95 offset:10272
	s_waitcnt lgkmcnt(3)
	v_mfma_f32_32x32x16_bf16 v[32:47], v[102:105], v[120:123], v[32:47]
	v_mfma_f32_32x32x16_bf16 v[16:31], v[106:109], v[120:123], v[16:31]
	v_mfma_f32_32x32x16_bf16 v[0:15], v[110:113], v[120:123], v[0:15]
	ds_read_b128 v[102:105], v95 offset:12832
	ds_read_b128 v[106:109], v95 offset:15392
	ds_read_b128 v[110:113], v95 offset:17952
	s_barrier
	s_waitcnt vmcnt(3)
	ds_write_b128 v93, v[74:77] offset:20480
	s_waitcnt vmcnt(2)
	ds_write_b128 v94, v[82:85] offset:20480
	s_waitcnt vmcnt(1)
	ds_write_b128 v93, v[86:89] offset:30720
	s_waitcnt vmcnt(0)
	ds_write_b128 v94, v[98:101] offset:30720
	global_load_dwordx4 v[74:77], v[66:67], off offset:1280
	global_load_dwordx4 v[82:85], v[68:69], off offset:1280
	global_load_dwordx4 v[86:89], v[72:73], off offset:256
	global_load_dwordx4 v[98:101], v[70:71], off offset:256
	s_waitcnt lgkmcnt(0)
	s_barrier
	v_mfma_f32_32x32x16_bf16 v[48:63], v[128:131], v[120:123], v[48:63]
	v_mfma_f32_32x32x16_bf16 v[32:47], v[102:105], v[124:127], v[32:47]
	v_mfma_f32_32x32x16_bf16 v[16:31], v[106:109], v[124:127], v[16:31]
	v_mfma_f32_32x32x16_bf16 v[0:15], v[110:113], v[124:127], v[0:15]
	v_mfma_f32_32x32x16_bf16 v[48:63], v[132:135], v[124:127], v[48:63]
	ds_read_b128 v[102:105], v95 offset:33280
	ds_read_b128 v[106:109], v95 offset:35840
	ds_read_b128 v[110:113], v95 offset:38400
	ds_read_b128 v[120:123], v96 offset:20480
	ds_read_b128 v[124:127], v96 offset:20512
	ds_read_b128 v[128:131], v95 offset:30720
	ds_read_b128 v[132:135], v95 offset:30752
	s_waitcnt lgkmcnt(3)
	v_mfma_f32_32x32x16_bf16 v[32:47], v[102:105], v[120:123], v[32:47]
	v_mfma_f32_32x32x16_bf16 v[16:31], v[106:109], v[120:123], v[16:31]
	v_mfma_f32_32x32x16_bf16 v[0:15], v[110:113], v[120:123], v[0:15]
	ds_read_b128 v[102:105], v95 offset:33312
	ds_read_b128 v[106:109], v95 offset:35872
	ds_read_b128 v[110:113], v95 offset:38432
	s_barrier
; #define MFMA(a, b, c) __builtin_amdgcn_mfma_f32_32x32x16_bf16((a), (b), (c), 0, 0, 0)
; template <int BM, int BN, int BK, int WAVES_M, int WAVES_N, int UNSWAP_FROM>
; DI void gemm_mainloop(const int tid, const bf16_t* __restrict__ A, int lda, const bf16_t* __restrict__ Bt, int ldb, int K, unsigned char* smem,
;                       f32x16 (&acc)[BM / WAVES_M / 32][BN / WAVES_N / 32]) {
;     ...
;     G_LOAD(0); G_STORE(0); __syncthreads();
;     for (int kt = 0; kt < nk; ++kt) {
;         const int buf = kt & 1;
;         if (kt + 1 < nk) G_LOAD(kt + 1);
;         const unsigned char* sa_ = smem + buf * STAGE; const unsigned char* sb_ = sa_ + A_ST;
; #pragma unroll
;         for (int ks = 0; ks < BK / 16; ++ks) {
;             bf16x8 af[WM], bfr[WN];
; #pragma unroll
;             for (int i = 0; i < WM; ++i) af[i] = *(const bf16x8*)(sa_ + (((wm * WM + i) * 32 + r) * LS + ks * 16 + h * 8) * 2);
; #pragma unroll
;             for (int j = 0; j < WN; ++j) bfr[j] = *(const bf16x8*)(sb_ + (((wn * WN + j) * 32 + r) * LS + ks * 16 + h * 8) * 2);
; #pragma unroll
;             for (int i = 0; i < WM; ++i)
; #pragma unroll
;                 for (int j = 0; j < WN; ++j) {
;                     if (j < UNSWAP_FROM) acc[i][j] = MFMA(bfr[j], af[i], acc[i][j]);
;                     else acc[i][j] = MFMA(af[i], bfr[j], acc[i][j]);
;                 }
;         }
;         if (kt + 1 < nk) G_STORE(buf ^ 1);
;         __syncthreads();
;     }
	s_waitcnt vmcnt(3)
	ds_write_b128 v93, v[74:77]
	s_waitcnt vmcnt(2)
	ds_write_b128 v94, v[82:85]
	s_waitcnt vmcnt(1)
	ds_write_b128 v93, v[86:89] offset:10240
	s_waitcnt vmcnt(0)
	ds_write_b128 v94, v[98:101] offset:10240
	global_load_dwordx4 v[74:77], v[66:67], off offset:1344
	global_load_dwordx4 v[82:85], v[68:69], off offset:1344
	global_load_dwordx4 v[86:89], v[72:73], off offset:320
	global_load_dwordx4 v[98:101], v[70:71], off offset:320
	s_waitcnt lgkmcnt(0)
	s_barrier
	v_mfma_f32_32x32x16_bf16 v[48:63], v[128:131], v[120:123], v[48:63]
	v_mfma_f32_32x32x16_bf16 v[32:47], v[102:105], v[124:127], v[32:47]
	v_mfma_f32_32x32x16_bf16 v[16:31], v[106:109], v[124:127], v[16:31]
	v_mfma_f32_32x32x16_bf16 v[0:15], v[110:113], v[124:127], v[0:15]
	v_mfma_f32_32x32x16_bf16 v[48:63], v[132:135], v[124:127], v[48:63]
	ds_read_b128 v[102:105], v95 offset:12800
	ds_read_b128 v[106:109], v95 offset:15360
	ds_read_b128 v[110:113], v95 offset:17920
	ds_read_b128 v[120:123], v96
	ds_read_b128 v[124:127], v96 offset:32
	ds_read_b128 v[128:131], v95 offset:10240
	ds_read_b128 v[132:135], v95 offset:10272
	s_waitcnt lgkmcnt(3)
	v_mfma_f32_32x32x16_bf16 v[32:47], v[102:105], v[120:123], v[32:47]
	v_mfma_f32_32x32x16_bf16 v[16:31], v[106:109], v[120:123], v[16:31]
	v_mfma_f32_32x32x16_bf16 v[0:15], v[110:113], v[120:123], v[0:15]
	ds_read_b128 v[102:105], v95 offset:12832
	ds_read_b128 v[106:109], v95 offset:15392
	ds_read_b128 v[110:113], v95 offset:17952
	s_barrier
	s_waitcnt vmcnt(3)
	ds_write_b128 v93, v[74:77] offset:20480
	s_waitcnt vmcnt(2)
	ds_write_b128 v94, v[82:85] offset:20480
	s_waitcnt vmcnt(1)
	ds_write_b128 v93, v[86:89] offset:30720
	s_waitcnt vmcnt(0)
	ds_write_b128 v94, v[98:101] offset:30720
	global_load_dwordx4 v[74:77], v[66:67], off offset:1408
	global_load_dwordx4 v[82:85], v[68:69], off offset:1408
	global_load_dwordx4 v[86:89], v[72:73], off offset:384
	global_load_dwordx4 v[98:101], v[70:71], off offset:384
	s_waitcnt lgkmcnt(0)
	s_barrier
	v_mfma_f32_32x32x16_bf16 v[48:63], v[128:131], v[120:123], v[48:63]
	v_mfma_f32_32x32x16_bf16 v[32:47], v[102:105], v[124:127], v[32:47]
	v_mfma_f32_32x32x16_bf16 v[16:31], v[106:109], v[124:127], v[16:31]
	v_mfma_f32_32x32x16_bf16 v[0:15], v[110:113], v[124:127], v[0:15]
	v_mfma_f32_32x32x16_bf16 v[48:63], v[132:135], v[124:127], v[48:63]
	ds_read_b128 v[102:105], v95 offset:33280
	ds_read_b128 v[106:109], v95 offset:35840
	ds_read_b128 v[110:113], v95 offset:38400
	ds_read_b128 v[120:123], v96 offset:20480
	ds_read_b128 v[124:127], v96 offset:20512
	ds_read_b128 v[128:131], v95 offset:30720
	ds_read_b128 v[132:135], v95 offset:30752
	s_waitcnt lgkmcnt(3)
	v_mfma_f32_32x32x16_bf16 v[32:47], v[102:105], v[120:123], v[32:47]
	v_mfma_f32_32x32x16_bf16 v[16:31], v[106:109], v[120:123], v[16:31]
	v_mfma_f32_32x32x16_bf16 v[0:15], v[110:113], v[120:123], v[0:15]
	ds_read_b128 v[102:105], v95 offset:33312
	ds_read_b128 v[106:109], v95 offset:35872
	ds_read_b128 v[110:113], v95 offset:38432
	s_barrier
	s_waitcnt vmcnt(3)
	ds_write_b128 v93, v[74:77]
	s_waitcnt vmcnt(2)
	ds_write_b128 v94, v[82:85]
	s_waitcnt vmcnt(1)
	ds_write_b128 v93, v[86:89] offset:10240
	s_waitcnt vmcnt(0)
	ds_write_b128 v94, v[98:101] offset:10240
	s_waitcnt lgkmcnt(0)
	s_barrier
	global_load_dwordx4 v[74:77], v[66:67], off offset:1472
	s_nop 0
	global_load_dwordx4 v[66:69], v[68:69], off offset:1472
	s_nop 0
	global_load_dwordx4 v[82:85], v[72:73], off offset:448
	s_nop 0
	global_load_dwordx4 v[70:73], v[70:71], off offset:448
	v_mfma_f32_32x32x16_bf16 v[48:63], v[128:131], v[120:123], v[48:63]
	v_mfma_f32_32x32x16_bf16 v[32:47], v[102:105], v[124:127], v[32:47]
	v_mfma_f32_32x32x16_bf16 v[16:31], v[106:109], v[124:127], v[16:31]
	v_mfma_f32_32x32x16_bf16 v[0:15], v[110:113], v[124:127], v[0:15]
	v_mfma_f32_32x32x16_bf16 v[48:63], v[132:135], v[124:127], v[48:63]
	ds_read_b128 v[86:89], v95 offset:12800
	ds_read_b128 v[98:101], v95 offset:15360
	ds_read_b128 v[102:105], v95 offset:17920
	ds_read_b128 v[106:109], v96
	ds_read_b128 v[110:113], v96 offset:32
	ds_read_b128 v[120:123], v95 offset:10240
	ds_read_b128 v[124:127], v95 offset:10272
	s_waitcnt lgkmcnt(3)
	v_mfma_f32_32x32x16_bf16 v[32:47], v[86:89], v[106:109], v[32:47]
	v_mfma_f32_32x32x16_bf16 v[16:31], v[98:101], v[106:109], v[16:31]
	v_mfma_f32_32x32x16_bf16 v[0:15], v[102:105], v[106:109], v[0:15]
	ds_read_b128 v[86:89], v95 offset:12832
	ds_read_b128 v[98:101], v95 offset:15392
	ds_read_b128 v[102:105], v95 offset:17952
	s_barrier
	s_waitcnt vmcnt(3)
	ds_write_b128 v93, v[74:77] offset:20480
	s_waitcnt vmcnt(2)
	ds_write_b128 v94, v[66:69] offset:20480
	s_waitcnt vmcnt(1)
	ds_write_b128 v93, v[82:85] offset:30720
	s_waitcnt vmcnt(0)
	ds_write_b128 v94, v[70:73] offset:30720
	s_waitcnt lgkmcnt(6)
	v_mfma_f32_32x32x16_bf16 v[32:47], v[86:89], v[110:113], v[32:47]
	s_waitcnt lgkmcnt(0)
	s_barrier
	v_mfma_f32_32x32x16_bf16 v[16:31], v[98:101], v[110:113], v[16:31]
	v_mfma_f32_32x32x16_bf16 v[0:15], v[102:105], v[110:113], v[0:15]
	ds_read_b128 v[66:69], v95 offset:33280
	ds_read_b128 v[70:73], v95 offset:35840
	ds_read_b128 v[74:77], v95 offset:38400
	ds_read_b128 v[82:85], v96 offset:20480
	ds_read_b128 v[86:89], v96 offset:20512
	ds_read_b128 v[98:101], v95 offset:30720
	ds_read_b128 v[102:105], v95 offset:30752
	v_mfma_f32_32x32x16_bf16 v[48:63], v[120:123], v[106:109], v[48:63]
	s_waitcnt lgkmcnt(3)
	v_mfma_f32_32x32x16_bf16 v[32:47], v[66:69], v[82:85], v[32:47]
	v_mfma_f32_32x32x16_bf16 v[16:31], v[70:73], v[82:85], v[16:31]
	v_mfma_f32_32x32x16_bf16 v[0:15], v[74:77], v[82:85], v[0:15]
	ds_read_b128 v[66:69], v95 offset:33312
	ds_read_b128 v[70:73], v95 offset:35872
	ds_read_b128 v[74:77], v95 offset:38432
	s_waitcnt lgkmcnt(0)
	s_barrier
	s_cmp_lg_u32 s10, 0
	s_cbranch_scc1 .Lkv_stg_end1
	s_barrier
